# attn v7: triple-buffered K (3rd buffer in free LDS), both groups prefetch K frags pre-barrier, counted vmcnt; no permlane; K swizzle 16-row
# speedup vs baseline: 1.0738x; 1.0007x over previous
; __device__ __forceinline__ int fresh_tid(int wave) { int z = 0; asm volatile("" : "+v"(z)); return wave * 64 + (int)__builtin_amdgcn_mbcnt_hi(~0u, __builtin_amdgcn_mbcnt_lo(~0u, (unsigned)z)); }
; __device__ __forceinline__ int v_st(int k, int c) { const int kk = (k & ~0xC) | ((k & 4) << 1) | ((k & 8) >> 1); return ((kk >> 3) * 4 + (c >> 5)) * 512 + ((kk & 7) * 32 + (c & 31)) * 2; }
; __device__ __forceinline__ int v_rd_base(int lane) { return ((lane & 3) << 3) | (((lane >> 2) & 3) << 6) | (((lane >> 4) & 1) << 5) | (((lane >> 5) & 1) << 8); }
; template <int MODE>
; __device__ __forceinline__ void attn_unit(const UnitArgs& A, char* lds, const int wave_) {
;     int tid_ = fresh_tid(wave_); asm volatile("" : "+v"(tid_));
;     const int tid = tid_, wid = __builtin_amdgcn_readfirstlane(tid >> 6), lane = tid & 63, r32 = lane & 31, hi = lane >> 5;
;     const int qb = wid & 3, half = wid >> 2;
;     if (wid >= 4) __builtin_amdgcn_s_setprio(1);
;     char* V_lds = lds; char* K_lds = lds + 2 * SHM_V;
;     float* ws = (float*)(lds + OFF_WS) + wid * 64; float* li_l = ws;
;     const float* lutA = (const float*)(lds + OFF_LUTA); const float* lutB = (const float*)(lds + OFF_LUTB);
;     float l_reg = 0; f32x16 o[4] = {}; bf16x8 qr[4];
;     { const bf16_t* Qw = A.Qb + (long)(qb * QBLK + r32) * NZ + half * 64 + hi * 8;
; #pragma unroll
;       for (int d0 = 0; d0 < 4; ++d0) qr[d0] = *reinterpret_cast<const bf16x8*>(Qw + d0 * 16); }
;     const int sr = tid >> 4, sc = (tid & 15) * 8, vst0 = v_st(sr, sc);
;     const int vbase = (int)(uintptr_t)V_lds + v_rd_base(lane) + (MODE == 0 ? 0 : half * 1024);
;     const int ldk = A.ldk; const unsigned ldoff = (unsigned)(sr * ldk + sc) * 2u;
;     struct { bf16x8 vs0, vs1; } sr_[1];
;     const unsigned kdoff = (unsigned)(sr * ldk + (((tid & 15) ^ (sr & 7)) * 8)) * 2u;
;     const unsigned kdst0 = (unsigned)__builtin_amdgcn_readfirstlane((int)((unsigned)(uintptr_t)K_lds + (unsigned)wid * 1024u));
;     ...
;     auto zone_of = [&](int t) -> int { const int k0 = 64 * t, qw0 = A.q0 + 32 * qb; return (k0 + 63 - qw0 <= -128) ? 0 : ((k0 - qw0 - 31 >= 128) ? 2 : 1); };
;     ...
;     SLOAD(0, 0); asm volatile("s_waitcnt vmcnt(0)" ::: "memory"); SWRITE(0, 0); SLOAD(0, 1); __syncthreads();
;     QK(pA0, pA1, K_lds, 0); post(pA0, pA1, 0); expHalf(pA0); expHalf(pA1);
.LBB0_314:
	s_add_i32 s84, s8, s7
	s_mul_i32 s3, s84, 0x1400
	s_mul_hi_u32 s2, s84, 0x1400
	s_add_u32 s17, s37, s3
	s_addc_u32 s18, s38, s2
	s_lshl_b32 s2, s6, 7
	s_ashr_i32 s3, s2, 31
	s_lshl_b64 s[2:3], s[2:3], 1
	s_add_u32 s24, s17, s2
	s_addc_u32 s25, s18, s3
	s_mul_i32 s31, s7, 0x1400
	s_mul_hi_u32 s30, s7, 0x1400
	s_add_u32 s6, s37, s31
	s_addc_u32 s7, s38, s30
	s_add_u32 s6, s6, s2
	s_addc_u32 s7, s7, s3
	s_and_b32 s18, s1, 3
	v_and_b32_e32 v156, 31, v40
	s_lshl_b32 s28, s18, 5
	v_or_b32_e32 v0, s28, v156
	s_ashr_i32 s17, s0, 8
	v_mul_u32_u24_e32 v144, 0x1400, v0
	v_lshl_add_u64 v[0:1], s[24:25], 0, v[144:145]
	s_lshl_b32 s24, s17, 6
	v_bfe_u32 v157, v40, 5, 1
	s_ashr_i32 s25, s24, 31
	v_lshl_add_u64 v[0:1], s[24:25], 1, v[0:1]
	v_lshlrev_b32_e32 v136, 4, v157
	v_mov_b32_e32 v137, v145
	v_lshl_add_u64 v[0:1], v[0:1], 0, v[136:137]
	global_load_dwordx4 v[108:111], v[0:1], off
	global_load_dwordx4 v[104:107], v[0:1], off offset:32
	global_load_dwordx4 v[100:103], v[0:1], off offset:64
	global_load_dwordx4 v[96:99], v[0:1], off offset:96
	s_add_u32 s24, s6, 0x400
	s_addc_u32 s25, s7, 0
	s_add_u32 s26, s6, 0x800
	s_addc_u32 s27, s7, 0
	v_and_b32_e32 v137, 63, v40
	v_lshlrev_b32_e32 v176, 8, v156
	v_and_b32_e32 v178, 15, v156
	v_lshlrev_b32_e32 v178, 4, v178
	s_lshl_b32 s99, s17, 7
	v_or_b32_e32 v179, s99, v136
	v_xor_b32_e32 v179, v179, v178
	v_add_u32_e32 v176, v176, v179
	v_add_u32_e32 v164, 0x8000, v176
	v_xor_b32_e32 v165, 32, v164
	v_xor_b32_e32 v166, 64, v164
	v_xor_b32_e32 v167, 0x60, v164
	v_and_b32_e32 v176, 3, v137
	v_lshlrev_b32_e32 v176, 3, v176
	v_bfe_u32 v178, v137, 2, 2
	v_lshlrev_b32_e32 v178, 6, v178
	v_bfe_u32 v179, v137, 4, 1
	v_lshlrev_b32_e32 v179, 5, v179
	v_bfe_u32 v180, v137, 5, 1
	v_lshlrev_b32_e32 v180, 8, v180
	v_or3_b32 v176, v176, v178, v179
	v_or_b32_e32 v168, v176, v180
	v_lshrrev_b32_e32 v176, 4, v40
	v_and_b32_e32 v178, 15, v40
	v_and_b32_e32 v179, 15, v176
	v_xor_b32_e32 v178, v178, v179
	v_lshlrev_b32_e32 v178, 4, v178
	v_mul_u32_u24_e32 v176, 0x1400, v176
	v_add_u32_e32 v169, v176, v178
	v_add_u32_e32 v170, 0x28000, v169
	v_bfe_u32 v178, v137, 2, 3
	s_bfe_u32 s99, s1, 0x10001
	s_lshl_b32 s99, s99, 3
	s_bfe_u32 s6, s1, 0x10002
	s_lshl_b32 s6, s6, 4
	s_or_b32 s99, s99, s6
	v_or_b32_e32 v178, s99, v178
	v_mul_u32_u24_e32 v178, 0x1400, v178
	s_and_b32 s99, s1, 1
	s_lshl_b32 s99, s99, 7
	v_bfe_u32 v176, v137, 5, 1
	v_lshlrev_b32_e32 v176, 6, v176
	v_and_b32_e32 v179, 3, v137
	v_lshlrev_b32_e32 v179, 4, v179
	v_add3_u32 v178, v178, v176, v179
	v_add_u32_e32 v171, s99, v178
	v_add_u32_e32 v172, 0x28000, v171
	s_lshl_b32 s33, s1, 10
	s_add_u32 s31, s33, 0x8000
	s_add_i32 s99, s8, s28
	s_sub_i32 s29, s99, 0xbf
	s_add_i32 s30, s99, 0x9f
	s_sub_i32 s35, 0x140, s99
	s_lshl_b32 s35, s35, 2
	s_add_i32 s35, s35, s19
	v_lshlrev_b32_e32 v176, 2, v157
	v_sub_u32_e32 v176, v176, v156
	v_lshlrev_b32_e32 v174, 2, v176
	v_mov_b32_e32 v176, s13
	v_sub_f32_e32 v178, s21, v176
	v_sub_f32_e32 v179, s20, v176
	s_xor_b32 s98, s13, 0x80000000
	s_sub_i32 s20, s22, 1
	v_readfirstlane_b32 s21, v178
	v_readfirstlane_b32 s22, v179
	s_mov_b32 s34, 0
	s_mov_b32 s23, 0
	s_cmp_le_i32 s23, s29
	s_cselect_b32 s9, s21, s98
	v_mov_b32_e32 v68, s9
	v_mov_b32_e32 v69, s9
	v_mov_b32_e32 v70, s9
	v_mov_b32_e32 v71, s9
	v_mov_b32_e32 v72, s9
	v_mov_b32_e32 v73, s9
	v_mov_b32_e32 v74, s9
	v_mov_b32_e32 v75, s9
	v_mov_b32_e32 v76, s9
	v_mov_b32_e32 v77, s9
	v_mov_b32_e32 v78, s9
	v_mov_b32_e32 v79, s9
	v_mov_b32_e32 v80, s9
	v_mov_b32_e32 v81, s9
	v_mov_b32_e32 v82, s9
	v_mov_b32_e32 v83, s9
	v_mov_b32_e32 v0, 0
	v_mov_b32_e32 v1, 0
	v_mov_b32_e32 v2, 0
	v_mov_b32_e32 v3, 0
	v_mov_b32_e32 v4, 0
	v_mov_b32_e32 v5, 0
	v_mov_b32_e32 v6, 0
	v_mov_b32_e32 v7, 0
	v_mov_b32_e32 v8, 0
	v_mov_b32_e32 v9, 0
	v_mov_b32_e32 v10, 0
	v_mov_b32_e32 v11, 0
	v_mov_b32_e32 v12, 0
	v_mov_b32_e32 v13, 0
	v_mov_b32_e32 v14, 0
	v_mov_b32_e32 v15, 0
	v_mov_b32_e32 v16, 0
	v_mov_b32_e32 v17, 0
	v_mov_b32_e32 v18, 0
	v_mov_b32_e32 v19, 0
	v_mov_b32_e32 v20, 0
	v_mov_b32_e32 v21, 0
	v_mov_b32_e32 v22, 0
	v_mov_b32_e32 v23, 0
	v_mov_b32_e32 v24, 0
	v_mov_b32_e32 v25, 0
	v_mov_b32_e32 v26, 0
	v_mov_b32_e32 v27, 0
	v_mov_b32_e32 v28, 0
	v_mov_b32_e32 v29, 0
	v_mov_b32_e32 v30, 0
	v_mov_b32_e32 v31, 0
	v_mov_b32_e32 v32, 0
	v_mov_b32_e32 v33, 0
	v_mov_b32_e32 v34, 0
	v_mov_b32_e32 v35, 0
	v_mov_b32_e32 v36, 0
	v_mov_b32_e32 v37, 0
	v_mov_b32_e32 v38, 0
	v_mov_b32_e32 v39, 0
	v_mov_b32_e32 v40, 0
	v_mov_b32_e32 v41, 0
	v_mov_b32_e32 v42, 0
	v_mov_b32_e32 v43, 0
	v_mov_b32_e32 v44, 0
	v_mov_b32_e32 v45, 0
	v_mov_b32_e32 v46, 0
	v_mov_b32_e32 v47, 0
	v_mov_b32_e32 v48, 0
	v_mov_b32_e32 v49, 0
	v_mov_b32_e32 v50, 0
	v_mov_b32_e32 v51, 0
	v_mov_b32_e32 v52, 0
	v_mov_b32_e32 v53, 0
	v_mov_b32_e32 v54, 0
	v_mov_b32_e32 v55, 0
	v_mov_b32_e32 v56, 0
	v_mov_b32_e32 v57, 0
	v_mov_b32_e32 v58, 0
	v_mov_b32_e32 v59, 0
	v_mov_b32_e32 v60, 0
	v_mov_b32_e32 v61, 0
	v_mov_b32_e32 v62, 0
	v_mov_b32_e32 v63, 0
	v_mov_b32_e32 v64, 0
	v_mov_b32_e32 v65, 0
	v_mov_b32_e32 v66, 0
	v_mov_b32_e32 v67, 0
	v_mov_b32_e32 v178, 0
	v_mov_b32_e32 v179, 0
	v_mov_b32_e32 v180, 0
	v_mov_b32_e32 v181, 0
	s_mov_b32 s100, 0x4000
	s_mov_b32 s101, 0x10200
	s_mov_b32 s32, 0xfffebe00
	s_mov_b32 m0, s31
	s_add_u32 s7, s31, 0x2000
	global_load_lds_dwordx4 v169, s[24:25]
	s_mov_b32 m0, s7
	s_add_u32 s31, s31, s100
	global_load_lds_dwordx4 v170, s[24:25]
	s_add_u32 s24, s24, 0x50000
	s_addc_u32 s25, s25, 0
	s_mov_b32 m0, s31
	s_add_u32 s7, s31, 0x2000
	global_load_lds_dwordx4 v169, s[24:25]
	s_mov_b32 m0, s7
	s_add_u32 s31, s31, s101
	global_load_lds_dwordx4 v170, s[24:25]
	s_add_u32 s24, s24, 0x50000
	s_addc_u32 s25, s25, 0
	s_mov_b32 m0, s31
	s_add_u32 s7, s31, 0x2000
	global_load_lds_dwordx4 v169, s[24:25]
	s_mov_b32 m0, s7
	s_add_u32 s31, s31, s32
	global_load_lds_dwordx4 v170, s[24:25]
	s_add_u32 s24, s24, 0x50000
	s_addc_u32 s25, s25, 0
	s_mov_b32 m0, s33
	s_add_u32 s7, s33, 0x2000
	global_load_lds_dwordx4 v171, s[26:27]
	s_mov_b32 m0, s7
	s_xor_b32 s33, s33, 0x4000
	global_load_lds_dwordx4 v172, s[26:27]
	s_add_u32 s26, s26, 0x50000
	s_addc_u32 s27, s27, 0
	s_waitcnt vmcnt(0)
	s_barrier
; #define SBAR() __builtin_amdgcn_sched_barrier(0)
; #define KFRAG(d0, row) (*reinterpret_cast<const bf16x8*>(Ks + KSWZ((row), (half * 64 + (d0) * 16 + hi * 8) * 2)))
; __device__ __forceinline__ void qkt(f32x16& p0, f32x16& p1, const char* Ks, const bf16x8* qr, float c0, int r32, int hi, int half) {
;     ...
;     bf16x8 a0 = KFRAG(0, r32), a1 = KFRAG(0, 32 + r32), b0 = KFRAG(1, r32), b1 = KFRAG(1, 32 + r32);
;     SBAR();
; #pragma unroll
;     for (int r = 0; r < 16; ++r) { p0[r] = c0; p1[r] = c0; }
;     SBAR();
;     p0 = __builtin_amdgcn_mfma_f32_32x32x16_bf16(a0, qr[0], p0, 0, 0, 0); p1 = __builtin_amdgcn_mfma_f32_32x32x16_bf16(a1, qr[0], p1, 0, 0, 0);
;     a0 = KFRAG(2, r32); a1 = KFRAG(2, 32 + r32);
;     SBAR();
;     p0 = __builtin_amdgcn_mfma_f32_32x32x16_bf16(b0, qr[1], p0, 0, 0, 0); p1 = __builtin_amdgcn_mfma_f32_32x32x16_bf16(b1, qr[1], p1, 0, 0, 0);
;     b0 = KFRAG(3, r32); b1 = KFRAG(3, 32 + r32);
;     SBAR();
;     p0 = __builtin_amdgcn_mfma_f32_32x32x16_bf16(a0, qr[2], p0, 0, 0, 0); p1 = __builtin_amdgcn_mfma_f32_32x32x16_bf16(a1, qr[2], p1, 0, 0, 0);
;     p0 = __builtin_amdgcn_mfma_f32_32x32x16_bf16(b0, qr[3], p0, 0, 0, 0); p1 = __builtin_amdgcn_mfma_f32_32x32x16_bf16(b1, qr[3], p1, 0, 0, 0);
;     ...
; }
	s_cmp_lg_u32 s17, 0
	s_cbranch_scc1 .Lat_g1
	s_setprio 0
	ds_read_b128 v[224:227], v164
	ds_read_b128 v[228:231], v164 offset:8192
	ds_read_b128 v[232:235], v165
	ds_read_b128 v[236:239], v165 offset:8192
	ds_read_b128 v[240:243], v166
	ds_read_b128 v[244:247], v166 offset:8192
	ds_read_b128 v[248:251], v167
	ds_read_b128 v[188:191], v167 offset:8192
	v_add_u32_e32 v164, s100, v164
	v_add_u32_e32 v165, s100, v165
	v_add_u32_e32 v166, s100, v166
	v_add_u32_e32 v167, s100, v167
	s_waitcnt lgkmcnt(7)
	v_mfma_f32_32x32x16_bf16 v[112:127], v[224:227], v[108:111], v[68:83]
	s_waitcnt lgkmcnt(6)
	v_mfma_f32_32x32x16_bf16 v[192:207], v[228:231], v[108:111], v[68:83]
	s_waitcnt lgkmcnt(5)
	v_mfma_f32_32x32x16_bf16 v[112:127], v[232:235], v[104:107], v[112:127]
	s_waitcnt lgkmcnt(4)
	v_mfma_f32_32x32x16_bf16 v[192:207], v[236:239], v[104:107], v[192:207]
	s_waitcnt lgkmcnt(3)
	v_mfma_f32_32x32x16_bf16 v[112:127], v[240:243], v[100:103], v[112:127]
	s_waitcnt lgkmcnt(2)
	v_mfma_f32_32x32x16_bf16 v[192:207], v[244:247], v[100:103], v[192:207]
	s_waitcnt lgkmcnt(1)
	v_mfma_f32_32x32x16_bf16 v[112:127], v[248:251], v[96:99], v[112:127]
	s_waitcnt lgkmcnt(0)
	v_mfma_f32_32x32x16_bf16 v[192:207], v[188:191], v[96:99], v[192:207]
	s_nop 7
	s_nop 3
	s_barrier

; #define SBAR() __builtin_amdgcn_sched_barrier(0)
; __device__ __forceinline__ void qkt(f32x16& p0, f32x16& p1, const char* Ks, const bf16x8* qr, float c0, int r32, int hi, int half) {
;     ...
;     bf16x8 a0 = KFRAG(0, r32), a1 = KFRAG(0, 32 + r32), b0 = KFRAG(1, r32), b1 = KFRAG(1, 32 + r32);
;     SBAR();
; #pragma unroll
;     for (int r = 0; r < 16; ++r) { p0[r] = c0; p1[r] = c0; }
;     SBAR();
;     p0 = __builtin_amdgcn_mfma_f32_32x32x16_bf16(a0, qr[0], p0, 0, 0, 0); p1 = __builtin_amdgcn_mfma_f32_32x32x16_bf16(a1, qr[0], p1, 0, 0, 0);
;     a0 = KFRAG(2, r32); a1 = KFRAG(2, 32 + r32);
;     SBAR();
;     p0 = __builtin_amdgcn_mfma_f32_32x32x16_bf16(b0, qr[1], p0, 0, 0, 0); p1 = __builtin_amdgcn_mfma_f32_32x32x16_bf16(b1, qr[1], p1, 0, 0, 0);
;     b0 = KFRAG(3, r32); b1 = KFRAG(3, 32 + r32);
;     SBAR();
;     p0 = __builtin_amdgcn_mfma_f32_32x32x16_bf16(a0, qr[2], p0, 0, 0, 0); p1 = __builtin_amdgcn_mfma_f32_32x32x16_bf16(a1, qr[2], p1, 0, 0, 0);
;     p0 = __builtin_amdgcn_mfma_f32_32x32x16_bf16(b0, qr[3], p0, 0, 0, 0); p1 = __builtin_amdgcn_mfma_f32_32x32x16_bf16(b1, qr[3], p1, 0, 0, 0);
;     ...
; }
; __device__ __forceinline__ int v_st(int k, int c) { const int kk = (k & ~0xC) | ((k & 4) << 1) | ((k & 8) >> 1); return ((kk >> 3) * 4 + (c >> 5)) * 512 + ((kk & 7) * 32 + (c & 31)) * 2; }
; __device__ __forceinline__ int v_rd_base(int lane) { return ((lane & 3) << 3) | (((lane >> 2) & 3) << 6) | (((lane >> 4) & 1) << 5) | (((lane >> 5) & 1) << 8); }
; template <int OFF> __device__ __forceinline__ s16x4 tr_read(int vb) { s16x4 r; asm volatile("ds_read_b64_tr_b16 %0, %1 offset:%2" : "=&v"(r) : "v"(vb), "i"(OFF) : "memory"); return r; }
; template <int MODE>
; __device__ __forceinline__ void attn_unit(const UnitArgs& A, char* lds, const int wave_) {
;     ...
;     for (int j = 1; j + 1 < NT; j += 2) {
;         SBAR(); QK(pB0, pB1, K_lds + SHM_K, j);
;         finishSM(pA0, pA1, l_reg, pa0, pa1, pa2, pa3); SBAR();
;         SLOAD(0, j + 1); SBAR();
;         post(pB0, pB1, j); PV(0, pB0, pB1);
;         __syncthreads(); SWAIT(); SWRITE(0, 0);
;         __syncthreads();
;         SBAR(); QK(pA0, pA1, K_lds, j + 1);
;         finishSM(pB0, pB1, l_reg, pa0, pa1, pa2, pa3); SBAR();
;         SLOAD(0, j + 2); SBAR();
;         post(pA0, pA1, j + 1); PV(1, pA0, pA1);
;         __syncthreads(); SWAIT(); SWRITE(1, 0);
;         __syncthreads();
.Lat_c0same_g0l:
	ds_read_b128 v[224:227], v164
	ds_read_b128 v[228:231], v164 offset:8192
	ds_read_b128 v[232:235], v165
	ds_read_b128 v[236:239], v165 offset:8192
	ds_read_b128 v[240:243], v166
	ds_read_b128 v[244:247], v166 offset:8192
	ds_read_b128 v[248:251], v167
	ds_read_b128 v[188:191], v167 offset:8192
	v_add_u32_e32 v164, s101, v164
	v_add_u32_e32 v165, s101, v165
	v_add_u32_e32 v166, s101, v166
	v_add_u32_e32 v167, s101, v167
	s_waitcnt vmcnt(2)
	s_barrier
	s_setprio 0
	s_waitcnt lgkmcnt(7)
	v_mfma_f32_32x32x16_bf16 v[112:127], v[224:227], v[108:111], v[68:83]
	s_waitcnt lgkmcnt(6)
	v_mfma_f32_32x32x16_bf16 v[192:207], v[228:231], v[108:111], v[68:83]
	ds_read_b64_tr_b16 v[84:85], v168 offset:0
	ds_read_b64_tr_b16 v[86:87], v168 offset:2048
	s_waitcnt lgkmcnt(7)
	v_mfma_f32_32x32x16_bf16 v[112:127], v[232:235], v[104:107], v[112:127]
	ds_read_b64_tr_b16 v[88:89], v168 offset:4096
	ds_read_b64_tr_b16 v[90:91], v168 offset:6144
	s_waitcnt lgkmcnt(8)
	v_mfma_f32_32x32x16_bf16 v[192:207], v[236:239], v[104:107], v[192:207]
	ds_read_b64_tr_b16 v[92:93], v168 offset:8192
	ds_read_b64_tr_b16 v[94:95], v168 offset:10240
	s_waitcnt lgkmcnt(9)
	v_mfma_f32_32x32x16_bf16 v[112:127], v[240:243], v[100:103], v[112:127]
	ds_read_b64_tr_b16 v[128:129], v168 offset:12288
	ds_read_b64_tr_b16 v[130:131], v168 offset:14336
	s_waitcnt lgkmcnt(10)
	v_mfma_f32_32x32x16_bf16 v[192:207], v[244:247], v[100:103], v[192:207]
	ds_read_b64_tr_b16 v[132:133], v168 offset:512
	ds_read_b64_tr_b16 v[134:135], v168 offset:2560
	s_waitcnt lgkmcnt(11)
	v_mfma_f32_32x32x16_bf16 v[112:127], v[248:251], v[96:99], v[112:127]
	ds_read_b64_tr_b16 v[140:141], v168 offset:4608
	ds_read_b64_tr_b16 v[142:143], v168 offset:6656
	s_waitcnt lgkmcnt(12)
	v_mfma_f32_32x32x16_bf16 v[192:207], v[188:191], v[96:99], v[192:207]
	ds_read_b64_tr_b16 v[152:153], v168 offset:8704
	ds_read_b64_tr_b16 v[154:155], v168 offset:10752
	s_waitcnt lgkmcnt(12)
	v_mfma_f32_32x32x16_bf16 v[0:15], v[208:211], v[84:87], v[0:15]
	ds_read_b64_tr_b16 v[160:161], v168 offset:12800
	ds_read_b64_tr_b16 v[162:163], v168 offset:14848
	s_waitcnt lgkmcnt(12)
	v_mfma_f32_32x32x16_bf16 v[0:15], v[212:215], v[88:91], v[0:15]
	ds_read_b64_tr_b16 v[84:85], v168 offset:1024
	ds_read_b64_tr_b16 v[86:87], v168 offset:3072
	s_waitcnt lgkmcnt(12)
	v_mfma_f32_32x32x16_bf16 v[0:15], v[216:219], v[92:95], v[0:15]
	ds_read_b64_tr_b16 v[88:89], v168 offset:5120
	ds_read_b64_tr_b16 v[90:91], v168 offset:7168
	s_waitcnt lgkmcnt(12)
	v_mfma_f32_32x32x16_bf16 v[0:15], v[220:223], v[128:131], v[0:15]
	ds_read_b64_tr_b16 v[92:93], v168 offset:9216
	ds_read_b64_tr_b16 v[94:95], v168 offset:11264
	s_waitcnt lgkmcnt(12)
	v_mfma_f32_32x32x16_bf16 v[16:31], v[208:211], v[132:135], v[16:31]
	ds_read_b64_tr_b16 v[128:129], v168 offset:13312
	ds_read_b64_tr_b16 v[130:131], v168 offset:15360
	s_mov_b32 m0, s33
	s_add_u32 s7, s33, 0x2000
	global_load_lds_dwordx4 v171, s[26:27]
	s_waitcnt lgkmcnt(12)
	v_mfma_f32_32x32x16_bf16 v[16:31], v[212:215], v[140:143], v[16:31]
	ds_read_b64_tr_b16 v[132:133], v168 offset:1536
	ds_read_b64_tr_b16 v[134:135], v168 offset:3584
	s_waitcnt lgkmcnt(12)
	v_mfma_f32_32x32x16_bf16 v[16:31], v[216:219], v[152:155], v[16:31]
	ds_read_b64_tr_b16 v[140:141], v168 offset:5632
	ds_read_b64_tr_b16 v[142:143], v168 offset:7680
	s_waitcnt lgkmcnt(12)
	v_mfma_f32_32x32x16_bf16 v[16:31], v[220:223], v[160:163], v[16:31]
	ds_read_b64_tr_b16 v[152:153], v168 offset:9728
	ds_read_b64_tr_b16 v[154:155], v168 offset:11776
	s_mov_b32 m0, s7
	s_xor_b32 s33, s33, 0x4000
	global_load_lds_dwordx4 v172, s[26:27]
	s_add_u32 s26, s26, 0x50000
	s_addc_u32 s27, s27, 0
	s_waitcnt lgkmcnt(12)
	v_mfma_f32_32x32x16_bf16 v[32:47], v[208:211], v[84:87], v[32:47]
	ds_read_b64_tr_b16 v[160:161], v168 offset:13824
	ds_read_b64_tr_b16 v[162:163], v168 offset:15872
	v_xor_b32_e32 v168, 0x4000, v168
	s_waitcnt lgkmcnt(12)
	v_mfma_f32_32x32x16_bf16 v[32:47], v[212:215], v[88:91], v[32:47]
	s_waitcnt lgkmcnt(10)
	v_mfma_f32_32x32x16_bf16 v[32:47], v[216:219], v[92:95], v[32:47]
	s_mov_b32 m0, s31
	s_add_u32 s7, s31, 0x2000
	global_load_lds_dwordx4 v169, s[24:25]
	s_waitcnt lgkmcnt(8)
	v_mfma_f32_32x32x16_bf16 v[32:47], v[220:223], v[128:131], v[32:47]
	s_waitcnt lgkmcnt(6)
	v_mfma_f32_32x32x16_bf16 v[48:63], v[208:211], v[132:135], v[48:63]
	s_waitcnt lgkmcnt(4)
	v_mfma_f32_32x32x16_bf16 v[48:63], v[212:215], v[140:143], v[48:63]
	s_mov_b32 m0, s7
	s_add_u32 s31, s31, s100
	global_load_lds_dwordx4 v170, s[24:25]
	s_add_u32 s24, s24, 0x50000
	s_addc_u32 s25, s25, 0
	s_waitcnt lgkmcnt(2)
	v_mfma_f32_32x32x16_bf16 v[48:63], v[216:219], v[152:155], v[48:63]
	s_waitcnt lgkmcnt(0)
	v_mfma_f32_32x32x16_bf16 v[48:63], v[220:223], v[160:163], v[48:63]
	s_add_i32 s34, s34, 1
	s_add_i32 s23, s23, 64
	s_addk_i32 s35, 0x100
	s_mov_b32 s8, s100
	s_mov_b32 s100, s101
	s_mov_b32 s101, s32
	s_mov_b32 s32, s8
	s_waitcnt vmcnt(4)
	s_barrier
; #define SBAR() __builtin_amdgcn_sched_barrier(0)
; #define QK(P0, P1, KS, t) do { float v_ = -A.mshift; if (MODE == 0) { const int z_ = zone_of(t); v_ += (z_ == 0 ? A.farL : (z_ == 2 ? A.farR : 0.f)); } \
;     qkt(P0, P1, KS, qr, v_, r32, hi, half); } while (0)
; template <int MODE>
; __device__ __forceinline__ void attn_unit(const UnitArgs& A, char* lds, const int wave_) {
;     ...
;     auto post = [&](f32x16& p0, f32x16& p1, int t) {
;         SBAR();
;         if (MODE == 0) {
;             if (zone_of(t) == 1) { const int k0 = 64 * t, qw0 = A.q0 + 32 * qb;
;                 const float* b = lutA + A.h * LUTA_STRIDE + (k0 - qw0 - r32 + 4 * hi + 320);
; #pragma unroll
;                 for (int r = 0; r < 16; ++r) { const int c = (r & 3) + 8 * (r >> 2); p0[r] += b[c]; p1[r] += b[32 + c]; } }
;     ...
;     SBAR(); QK(pB0, pB1, K_lds + SHM_K, NT - 1);
;     finishSM(pA0, pA1, l_reg, pa0, pa1, pa2, pa3); SBAR();
;     post(pB0, pB1, NT - 1); PV(0, pB0, pB1);
	s_cmp_lt_u32 s34, s20
	s_cbranch_scc1 .Lat_g0_loop
	s_setprio 1
	s_cmp_gt_i32 s23, s29
	s_cselect_b32 s99, 1, 0
	s_cmp_lt_i32 s23, s30
	s_cselect_b32 s6, 1, 0
	s_and_b32 s99, s99, s6
	s_cbranch_scc0 .Lat_far_g0p
	v_add_u32_e32 v186, s35, v174
	ds_read2_b32 v[224:225], v186 offset0:0 offset1:1
	ds_read2_b32 v[226:227], v186 offset0:2 offset1:3
	ds_read2_b32 v[228:229], v186 offset0:8 offset1:9
	ds_read2_b32 v[230:231], v186 offset0:10 offset1:11
	ds_read2_b32 v[232:233], v186 offset0:16 offset1:17
	ds_read2_b32 v[234:235], v186 offset0:18 offset1:19
	ds_read2_b32 v[236:237], v186 offset0:24 offset1:25
	ds_read2_b32 v[238:239], v186 offset0:26 offset1:27
	s_waitcnt lgkmcnt(4)
	ds_read2_b32 v[240:241], v186 offset0:32 offset1:33
	ds_read2_b32 v[242:243], v186 offset0:34 offset1:35
	ds_read2_b32 v[244:245], v186 offset0:40 offset1:41
	ds_read2_b32 v[246:247], v186 offset0:42 offset1:43
	ds_read2_b32 v[248:249], v186 offset0:48 offset1:49
	ds_read2_b32 v[250:251], v186 offset0:50 offset1:51
	ds_read2_b32 v[188:189], v186 offset0:56 offset1:57
	ds_read2_b32 v[190:191], v186 offset0:58 offset1:59
	s_waitcnt lgkmcnt(8)
	v_add_f32_e32 v112, v112, v224
	v_add_f32_e32 v113, v113, v225
	v_add_f32_e32 v114, v114, v226
	v_add_f32_e32 v115, v115, v227
	v_add_f32_e32 v116, v116, v228
	v_add_f32_e32 v117, v117, v229
	v_add_f32_e32 v118, v118, v230
	v_add_f32_e32 v119, v119, v231
	v_add_f32_e32 v120, v120, v232
	v_add_f32_e32 v121, v121, v233
	v_add_f32_e32 v122, v122, v234
	v_add_f32_e32 v123, v123, v235
	v_add_f32_e32 v124, v124, v236
	v_add_f32_e32 v125, v125, v237
	v_add_f32_e32 v126, v126, v238
	v_add_f32_e32 v127, v127, v239
	s_waitcnt lgkmcnt(0)
	v_add_f32_e32 v192, v192, v240
	v_add_f32_e32 v193, v193, v241
	v_add_f32_e32 v194, v194, v242
	v_add_f32_e32 v195, v195, v243
	v_add_f32_e32 v196, v196, v244
	v_add_f32_e32 v197, v197, v245
	v_add_f32_e32 v198, v198, v246
	v_add_f32_e32 v199, v199, v247
	v_add_f32_e32 v200, v200, v248
	v_add_f32_e32 v201, v201, v249
	v_add_f32_e32 v202, v202, v250
	v_add_f32_e32 v203, v203, v251
	v_add_f32_e32 v204, v204, v188
	v_add_f32_e32 v205, v205, v189
	v_add_f32_e32 v206, v206, v190
	v_add_f32_e32 v207, v207, v191

; #define SBAR() __builtin_amdgcn_sched_barrier(0)
; #define KFRAG(d0, row) (*reinterpret_cast<const bf16x8*>(Ks + KSWZ((row), (half * 64 + (d0) * 16 + hi * 8) * 2)))
; __device__ __forceinline__ void qkt(f32x16& p0, f32x16& p1, const char* Ks, const bf16x8* qr, float c0, int r32, int hi, int half) {
;     ...
;     bf16x8 a0 = KFRAG(0, r32), a1 = KFRAG(0, 32 + r32), b0 = KFRAG(1, r32), b1 = KFRAG(1, 32 + r32);
;     SBAR();
; #pragma unroll
;     for (int r = 0; r < 16; ++r) { p0[r] = c0; p1[r] = c0; }
;     SBAR();
;     p0 = __builtin_amdgcn_mfma_f32_32x32x16_bf16(a0, qr[0], p0, 0, 0, 0); p1 = __builtin_amdgcn_mfma_f32_32x32x16_bf16(a1, qr[0], p1, 0, 0, 0);
;     a0 = KFRAG(2, r32); a1 = KFRAG(2, 32 + r32);
;     SBAR();
;     p0 = __builtin_amdgcn_mfma_f32_32x32x16_bf16(b0, qr[1], p0, 0, 0, 0); p1 = __builtin_amdgcn_mfma_f32_32x32x16_bf16(b1, qr[1], p1, 0, 0, 0);
;     b0 = KFRAG(3, r32); b1 = KFRAG(3, 32 + r32);
;     SBAR();
;     p0 = __builtin_amdgcn_mfma_f32_32x32x16_bf16(a0, qr[2], p0, 0, 0, 0); p1 = __builtin_amdgcn_mfma_f32_32x32x16_bf16(a1, qr[2], p1, 0, 0, 0);
;     p0 = __builtin_amdgcn_mfma_f32_32x32x16_bf16(b0, qr[3], p0, 0, 0, 0); p1 = __builtin_amdgcn_mfma_f32_32x32x16_bf16(b1, qr[3], p1, 0, 0, 0);
;     ...
; }
.Lat_g1:
	s_barrier
	s_setprio 0
	ds_read_b128 v[224:227], v164
	ds_read_b128 v[228:231], v164 offset:8192
	ds_read_b128 v[232:235], v165
	ds_read_b128 v[236:239], v165 offset:8192
	ds_read_b128 v[240:243], v166
	ds_read_b128 v[244:247], v166 offset:8192
	ds_read_b128 v[248:251], v167
	ds_read_b128 v[188:191], v167 offset:8192
	v_add_u32_e32 v164, s100, v164
	v_add_u32_e32 v165, s100, v165
	v_add_u32_e32 v166, s100, v166
	v_add_u32_e32 v167, s100, v167
	s_waitcnt lgkmcnt(7)
	v_mfma_f32_32x32x16_bf16 v[112:127], v[224:227], v[108:111], v[68:83]
	s_waitcnt lgkmcnt(6)
	v_mfma_f32_32x32x16_bf16 v[192:207], v[228:231], v[108:111], v[68:83]
	s_waitcnt lgkmcnt(5)
	v_mfma_f32_32x32x16_bf16 v[112:127], v[232:235], v[104:107], v[112:127]
	s_waitcnt lgkmcnt(4)
	v_mfma_f32_32x32x16_bf16 v[192:207], v[236:239], v[104:107], v[192:207]
	s_waitcnt lgkmcnt(3)
	v_mfma_f32_32x32x16_bf16 v[112:127], v[240:243], v[100:103], v[112:127]
	s_waitcnt lgkmcnt(2)
	v_mfma_f32_32x32x16_bf16 v[192:207], v[244:247], v[100:103], v[192:207]
	s_waitcnt lgkmcnt(1)
	v_mfma_f32_32x32x16_bf16 v[112:127], v[248:251], v[96:99], v[112:127]
	s_waitcnt lgkmcnt(0)
	v_mfma_f32_32x32x16_bf16 v[192:207], v[188:191], v[96:99], v[192:207]
	s_nop 7
	s_nop 3
	s_barrier

; #define SBAR() __builtin_amdgcn_sched_barrier(0)
; #define KFRAG(d0, row) (*reinterpret_cast<const bf16x8*>(Ks + KSWZ((row), (half * 64 + (d0) * 16 + hi * 8) * 2)))
; __device__ __forceinline__ void expHalf(f32x16& p0) {
; #pragma unroll
;     for (int r = 0; r < 16; ++r) p0[r] = __builtin_amdgcn_exp2f(p0[r]);
; }
; __device__ __forceinline__ void finishSM(f32x16& p0, f32x16& p1, float& l_reg, bf16x8& pa0, bf16x8& pa1, bf16x8& pa2, bf16x8& pa3) {
;     float ps = 0;
; #pragma unroll
;     for (int r = 0; r < 16; ++r) ps += p0[r];
; #pragma unroll
;     for (int r = 0; r < 16; ++r) ps += p1[r];
;     l_reg += ps;
;     ...
;     PK4(p0, 0, pa0); PK4(p0, 8, pa1); PK4(p1, 0, pa2); PK4(p1, 8, pa3);
;     ...
; }
; __device__ __forceinline__ void qkt(f32x16& p0, f32x16& p1, const char* Ks, const bf16x8* qr, float c0, int r32, int hi, int half) {
;     ...
;     bf16x8 a0 = KFRAG(0, r32), a1 = KFRAG(0, 32 + r32), b0 = KFRAG(1, r32), b1 = KFRAG(1, 32 + r32);
;     SBAR();
; #pragma unroll
;     for (int r = 0; r < 16; ++r) { p0[r] = c0; p1[r] = c0; }
;     SBAR();
;     p0 = __builtin_amdgcn_mfma_f32_32x32x16_bf16(a0, qr[0], p0, 0, 0, 0); p1 = __builtin_amdgcn_mfma_f32_32x32x16_bf16(a1, qr[0], p1, 0, 0, 0);
;     a0 = KFRAG(2, r32); a1 = KFRAG(2, 32 + r32);
;     SBAR();
;     p0 = __builtin_amdgcn_mfma_f32_32x32x16_bf16(b0, qr[1], p0, 0, 0, 0); p1 = __builtin_amdgcn_mfma_f32_32x32x16_bf16(b1, qr[1], p1, 0, 0, 0);
;     b0 = KFRAG(3, r32); b1 = KFRAG(3, 32 + r32);
;     SBAR();
;     p0 = __builtin_amdgcn_mfma_f32_32x32x16_bf16(a0, qr[2], p0, 0, 0, 0); p1 = __builtin_amdgcn_mfma_f32_32x32x16_bf16(a1, qr[2], p1, 0, 0, 0);
;     p0 = __builtin_amdgcn_mfma_f32_32x32x16_bf16(b0, qr[3], p0, 0, 0, 0); p1 = __builtin_amdgcn_mfma_f32_32x32x16_bf16(b1, qr[3], p1, 0, 0, 0);
;     ...
; }
; template <int MODE>
; __device__ __forceinline__ void attn_unit(const UnitArgs& A, char* lds, const int wave_) {
;     ...
;     auto zone_of = [&](int t) -> int { const int k0 = 64 * t, qw0 = A.q0 + 32 * qb; return (k0 + 63 - qw0 <= -128) ? 0 : ((k0 - qw0 - 31 >= 128) ? 2 : 1); };
.Lat_far_g1l:
	s_mov_b32 m0, s33
	s_add_u32 s7, s33, 0x2000
	global_load_lds_dwordx4 v171, s[26:27]
	v_exp_f32_e32 v112, v112
	v_exp_f32_e32 v113, v113
	v_exp_f32_e32 v114, v114
	v_exp_f32_e32 v115, v115
	v_exp_f32_e32 v116, v116
	v_exp_f32_e32 v117, v117
	v_exp_f32_e32 v118, v118
	v_exp_f32_e32 v119, v119
	s_mov_b32 m0, s7
	s_xor_b32 s33, s33, 0x4000
	global_load_lds_dwordx4 v172, s[26:27]
	s_add_u32 s26, s26, 0x50000
	s_addc_u32 s27, s27, 0
	v_exp_f32_e32 v120, v120
	v_exp_f32_e32 v121, v121
	v_exp_f32_e32 v122, v122
	v_exp_f32_e32 v123, v123
	v_exp_f32_e32 v124, v124
	v_exp_f32_e32 v125, v125
	v_exp_f32_e32 v126, v126
	v_exp_f32_e32 v127, v127
	s_mov_b32 m0, s31
	s_add_u32 s7, s31, 0x2000
	global_load_lds_dwordx4 v169, s[24:25]
	v_exp_f32_e32 v192, v192
	v_add_f32_e32 v64, v64, v112
	v_exp_f32_e32 v193, v193
	v_add_f32_e32 v65, v65, v113
	v_exp_f32_e32 v194, v194
	v_add_f32_e32 v66, v66, v114
	v_exp_f32_e32 v195, v195
	v_add_f32_e32 v67, v67, v115
	v_exp_f32_e32 v196, v196
	v_add_f32_e32 v64, v64, v116
	v_exp_f32_e32 v197, v197
	v_add_f32_e32 v65, v65, v117
	s_mov_b32 m0, s7
	s_add_u32 s31, s31, s100
	global_load_lds_dwordx4 v170, s[24:25]
	s_add_u32 s24, s24, 0x50000
	s_addc_u32 s25, s25, 0
	v_exp_f32_e32 v198, v198
	v_add_f32_e32 v66, v66, v118
	v_exp_f32_e32 v199, v199
	v_add_f32_e32 v67, v67, v119
	v_exp_f32_e32 v200, v200
	v_add_f32_e32 v64, v64, v120
	v_exp_f32_e32 v201, v201
	v_add_f32_e32 v65, v65, v121
	v_exp_f32_e32 v202, v202
	v_add_f32_e32 v66, v66, v122
	v_exp_f32_e32 v203, v203
	v_add_f32_e32 v67, v67, v123
	v_exp_f32_e32 v204, v204
	v_add_f32_e32 v64, v64, v124
	v_exp_f32_e32 v205, v205
	v_add_f32_e32 v65, v65, v125
	v_exp_f32_e32 v206, v206
	v_add_f32_e32 v66, v66, v126
	v_exp_f32_e32 v207, v207
	v_add_f32_e32 v67, v67, v127
	v_cvt_pk_bf16_f32 v208, v112, v113
	v_cvt_pk_bf16_f32 v209, v114, v115
	v_cvt_pk_bf16_f32 v210, v116, v117
	v_cvt_pk_bf16_f32 v211, v118, v119
	v_cvt_pk_bf16_f32 v212, v120, v121
	v_cvt_pk_bf16_f32 v213, v122, v123
	v_cvt_pk_bf16_f32 v214, v124, v125
	v_cvt_pk_bf16_f32 v215, v126, v127
	v_add_f32_e32 v64, v64, v192
	v_add_f32_e32 v65, v65, v193
	v_add_f32_e32 v66, v66, v194
	v_add_f32_e32 v67, v67, v195
	v_add_f32_e32 v64, v64, v196
	v_add_f32_e32 v65, v65, v197
	v_add_f32_e32 v66, v66, v198
	v_add_f32_e32 v67, v67, v199
	v_add_f32_e32 v64, v64, v200
	v_add_f32_e32 v65, v65, v201
	v_add_f32_e32 v66, v66, v202
	v_add_f32_e32 v67, v67, v203
	v_add_f32_e32 v64, v64, v204
	v_add_f32_e32 v65, v65, v205
	v_add_f32_e32 v66, v66, v206
	v_add_f32_e32 v67, v67, v207
	v_cvt_pk_bf16_f32 v216, v192, v193
	v_cvt_pk_bf16_f32 v217, v194, v195
	v_cvt_pk_bf16_f32 v218, v196, v197
	v_cvt_pk_bf16_f32 v219, v198, v199
	v_cvt_pk_bf16_f32 v220, v200, v201
	v_cvt_pk_bf16_f32 v221, v202, v203
	v_cvt_pk_bf16_f32 v222, v204, v205
	v_cvt_pk_bf16_f32 v223, v206, v207
	s_add_i32 s99, s23, 64
	s_cmp_ge_i32 s99, s30
	s_cselect_b32 s6, s22, s98
	s_cmp_le_i32 s99, s29
	s_cselect_b32 s6, s21, s6
	s_nop 0
	s_cmp_lg_u32 s6, s9
	s_cbranch_scc0 .Lat_c0same_g1l
	s_mov_b32 s9, s6
	v_mov_b32_e32 v68, s9
	v_mov_b32_e32 v69, s9
	v_mov_b32_e32 v70, s9
	v_mov_b32_e32 v71, s9
	v_mov_b32_e32 v72, s9
	v_mov_b32_e32 v73, s9
	v_mov_b32_e32 v74, s9
	v_mov_b32_e32 v75, s9
	v_mov_b32_e32 v76, s9
	v_mov_b32_e32 v77, s9
	v_mov_b32_e32 v78, s9
	v_mov_b32_e32 v79, s9
	v_mov_b32_e32 v80, s9
	v_mov_b32_e32 v81, s9
	v_mov_b32_e32 v82, s9
	v_mov_b32_e32 v83, s9
.Lat_c0same_g1l:
	ds_read_b128 v[224:227], v164
	ds_read_b128 v[228:231], v164 offset:8192
	ds_read_b128 v[232:235], v165
	ds_read_b128 v[236:239], v165 offset:8192
	ds_read_b128 v[240:243], v166
	ds_read_b128 v[244:247], v166 offset:8192
	ds_read_b128 v[248:251], v167
	ds_read_b128 v[188:191], v167 offset:8192
	v_add_u32_e32 v164, s101, v164
	v_add_u32_e32 v165, s101, v165
	v_add_u32_e32 v166, s101, v166
	v_add_u32_e32 v167, s101, v167
	s_waitcnt vmcnt(4)
	s_barrier
	s_setprio 0
	s_waitcnt lgkmcnt(7)
	v_mfma_f32_32x32x16_bf16 v[112:127], v[224:227], v[108:111], v[68:83]
	s_waitcnt lgkmcnt(6)
	v_mfma_f32_32x32x16_bf16 v[192:207], v[228:231], v[108:111], v[68:83]
	ds_read_b64_tr_b16 v[84:85], v168 offset:0
	ds_read_b64_tr_b16 v[86:87], v168 offset:2048
	s_waitcnt lgkmcnt(7)
	v_mfma_f32_32x32x16_bf16 v[112:127], v[232:235], v[104:107], v[112:127]
	ds_read_b64_tr_b16 v[88:89], v168 offset:4096
	ds_read_b64_tr_b16 v[90:91], v168 offset:6144
	s_waitcnt lgkmcnt(8)
	v_mfma_f32_32x32x16_bf16 v[192:207], v[236:239], v[104:107], v[192:207]
	ds_read_b64_tr_b16 v[92:93], v168 offset:8192
	ds_read_b64_tr_b16 v[94:95], v168 offset:10240
	s_waitcnt lgkmcnt(9)
	v_mfma_f32_32x32x16_bf16 v[112:127], v[240:243], v[100:103], v[112:127]
	ds_read_b64_tr_b16 v[128:129], v168 offset:12288
	ds_read_b64_tr_b16 v[130:131], v168 offset:14336
	s_waitcnt lgkmcnt(10)
	v_mfma_f32_32x32x16_bf16 v[192:207], v[244:247], v[100:103], v[192:207]
	ds_read_b64_tr_b16 v[132:133], v168 offset:512
	ds_read_b64_tr_b16 v[134:135], v168 offset:2560
	s_waitcnt lgkmcnt(11)
	v_mfma_f32_32x32x16_bf16 v[112:127], v[248:251], v[96:99], v[112:127]
	ds_read_b64_tr_b16 v[140:141], v168 offset:4608
	ds_read_b64_tr_b16 v[142:143], v168 offset:6656
	s_waitcnt lgkmcnt(12)
	v_mfma_f32_32x32x16_bf16 v[192:207], v[188:191], v[96:99], v[192:207]
	ds_read_b64_tr_b16 v[152:153], v168 offset:8704
	ds_read_b64_tr_b16 v[154:155], v168 offset:10752
	s_waitcnt lgkmcnt(12)
	v_mfma_f32_32x32x16_bf16 v[0:15], v[208:211], v[84:87], v[0:15]
	ds_read_b64_tr_b16 v[160:161], v168 offset:12800
	ds_read_b64_tr_b16 v[162:163], v168 offset:14848
	s_waitcnt lgkmcnt(12)
	v_mfma_f32_32x32x16_bf16 v[0:15], v[212:215], v[88:91], v[0:15]
	ds_read_b64_tr_b16 v[84:85], v168 offset:1024
	ds_read_b64_tr_b16 v[86:87], v168 offset:3072
	s_waitcnt lgkmcnt(12)
; #define SBAR() __builtin_amdgcn_sched_barrier(0)
; #define PVLOAD(D0, X) do { X[0] = tr_read<v_rd_off(D0, 0, 0)>(vb); X[1] = tr_read<v_rd_off(D0, 0, 1)>(vb); X[2] = tr_read<v_rd_off(D0, 1, 0)>(vb); X[3] = tr_read<v_rd_off(D0, 1, 1)>(vb); \
;     X[4] = tr_read<v_rd_off(D0, 2, 0)>(vb); X[5] = tr_read<v_rd_off(D0, 2, 1)>(vb); X[6] = tr_read<v_rd_off(D0, 3, 0)>(vb); X[7] = tr_read<v_rd_off(D0, 3, 1)>(vb); } while (0)
; #define PVMMA(OD, X) do { OD = __builtin_amdgcn_mfma_f32_32x32x16_bf16(pa0, PVPK(X[0], X[1]), OD, 0, 0, 0); OD = __builtin_amdgcn_mfma_f32_32x32x16_bf16(pa1, PVPK(X[2], X[3]), OD, 0, 0, 0); \
;     OD = __builtin_amdgcn_mfma_f32_32x32x16_bf16(pa2, PVPK(X[4], X[5]), OD, 0, 0, 0); OD = __builtin_amdgcn_mfma_f32_32x32x16_bf16(pa3, PVPK(X[6], X[7]), OD, 0, 0, 0); } while (0)
; #define PVWAIT() do { asm volatile("s_waitcnt lgkmcnt(0)" ::: "memory"); SBAR(); } while (0)
; template <int OFF> __device__ __forceinline__ s16x4 tr_read(int vb) { s16x4 r; asm volatile("ds_read_b64_tr_b16 %0, %1 offset:%2" : "=&v"(r) : "v"(vb), "i"(OFF) : "memory"); return r; }
; template <int NB> __device__ __forceinline__ void pv_blocks(f32x16* o, int vb, bf16x8 pa0, bf16x8 pa1, bf16x8 pa2, bf16x8 pa3, f32x16& pe0, f32x16& pe1) {
;     s16x4 x[8], y[8];
;     ...
;     PVLOAD(0, x); PVWAIT();
;     if (NB == 4) {
;         PVLOAD(1, y); SBAR(); PVMMA(o[0], x); PVEXP(pe0, 0, 8); SBAR(); PVWAIT();
;         PVLOAD(2, x); SBAR(); PVMMA(o[1], y); PVEXP(pe0, 8, 8); SBAR(); PVWAIT();
;         PVLOAD(3, y); SBAR(); PVMMA(o[2], x); PVEXP(pe1, 0, 8); SBAR(); PVWAIT();
;         PVMMA(o[3], y); PVEXP(pe1, 8, 8);
;     } else {
;         PVLOAD(1, y); SBAR(); PVMMA(o[0], x); PVEXP(pe0, 0, 16); SBAR(); PVWAIT();
;         PVMMA(o[1], y); PVEXP(pe1, 0, 16);
;     }
;     ...
; }
; template <int MODE>
; __device__ __forceinline__ void attn_unit(const UnitArgs& A, char* lds, const int wave_) {
;     ...
;     auto post = [&](f32x16& p0, f32x16& p1, int t) {
;         SBAR();
;         if (MODE == 0) {
;             if (zone_of(t) == 1) { const int k0 = 64 * t, qw0 = A.q0 + 32 * qb;
;                 const float* b = lutA + A.h * LUTA_STRIDE + (k0 - qw0 - r32 + 4 * hi + 320);
; #pragma unroll
;                 for (int r = 0; r < 16; ++r) { const int c = (r & 3) + 8 * (r >> 2); p0[r] += b[c]; p1[r] += b[32 + c]; } }
	v_mfma_f32_32x32x16_bf16 v[0:15], v[216:219], v[92:95], v[0:15]
	ds_read_b64_tr_b16 v[88:89], v168 offset:5120
	ds_read_b64_tr_b16 v[90:91], v168 offset:7168
	s_waitcnt lgkmcnt(12)
	v_mfma_f32_32x32x16_bf16 v[0:15], v[220:223], v[128:131], v[0:15]
	ds_read_b64_tr_b16 v[92:93], v168 offset:9216
	ds_read_b64_tr_b16 v[94:95], v168 offset:11264
	s_waitcnt lgkmcnt(12)
	v_mfma_f32_32x32x16_bf16 v[16:31], v[208:211], v[132:135], v[16:31]
	ds_read_b64_tr_b16 v[128:129], v168 offset:13312
	ds_read_b64_tr_b16 v[130:131], v168 offset:15360
	s_waitcnt lgkmcnt(12)
	v_mfma_f32_32x32x16_bf16 v[16:31], v[212:215], v[140:143], v[16:31]
	ds_read_b64_tr_b16 v[132:133], v168 offset:1536
	ds_read_b64_tr_b16 v[134:135], v168 offset:3584
	s_waitcnt lgkmcnt(12)
	v_mfma_f32_32x32x16_bf16 v[16:31], v[216:219], v[152:155], v[16:31]
	ds_read_b64_tr_b16 v[140:141], v168 offset:5632
	ds_read_b64_tr_b16 v[142:143], v168 offset:7680
	s_waitcnt lgkmcnt(12)
	v_mfma_f32_32x32x16_bf16 v[16:31], v[220:223], v[160:163], v[16:31]
	ds_read_b64_tr_b16 v[152:153], v168 offset:9728
	ds_read_b64_tr_b16 v[154:155], v168 offset:11776
	s_waitcnt lgkmcnt(12)
	v_mfma_f32_32x32x16_bf16 v[32:47], v[208:211], v[84:87], v[32:47]
	ds_read_b64_tr_b16 v[160:161], v168 offset:13824
	ds_read_b64_tr_b16 v[162:163], v168 offset:15872
	v_xor_b32_e32 v168, 0x4000, v168
	s_waitcnt lgkmcnt(12)
	v_mfma_f32_32x32x16_bf16 v[32:47], v[212:215], v[88:91], v[32:47]
	s_waitcnt lgkmcnt(10)
	v_mfma_f32_32x32x16_bf16 v[32:47], v[216:219], v[92:95], v[32:47]
	s_waitcnt lgkmcnt(8)
	v_mfma_f32_32x32x16_bf16 v[32:47], v[220:223], v[128:131], v[32:47]
	s_waitcnt lgkmcnt(6)
	v_mfma_f32_32x32x16_bf16 v[48:63], v[208:211], v[132:135], v[48:63]
	s_waitcnt lgkmcnt(4)
	v_mfma_f32_32x32x16_bf16 v[48:63], v[212:215], v[140:143], v[48:63]
	s_waitcnt lgkmcnt(2)
	v_mfma_f32_32x32x16_bf16 v[48:63], v[216:219], v[152:155], v[48:63]
	s_waitcnt lgkmcnt(0)
	v_mfma_f32_32x32x16_bf16 v[48:63], v[220:223], v[160:163], v[48:63]
	s_add_i32 s34, s34, 1
	s_add_i32 s23, s23, 64
	s_addk_i32 s35, 0x100
	s_mov_b32 s8, s100
	s_mov_b32 s100, s101
	s_mov_b32 s101, s32
	s_mov_b32 s32, s8
	s_waitcnt vmcnt(2)
	s_barrier
	s_cmp_lt_u32 s34, s20
	s_cbranch_scc1 .Lat_g1_loop
	s_setprio 1
	s_cmp_gt_i32 s23, s29
	s_cselect_b32 s99, 1, 0
	s_cmp_lt_i32 s23, s30
	s_cselect_b32 s6, 1, 0
	s_and_b32 s99, s99, s6
	s_cbranch_scc0 .Lat_far_g1p
	v_add_u32_e32 v186, s35, v174
	ds_read2_b32 v[224:225], v186 offset0:0 offset1:1
	ds_read2_b32 v[226:227], v186 offset0:2 offset1:3
	ds_read2_b32 v[228:229], v186 offset0:8 offset1:9
	ds_read2_b32 v[230:231], v186 offset0:10 offset1:11
	ds_read2_b32 v[232:233], v186 offset0:16 offset1:17
	ds_read2_b32 v[234:235], v186 offset0:18 offset1:19
	ds_read2_b32 v[236:237], v186 offset0:24 offset1:25
	ds_read2_b32 v[238:239], v186 offset0:26 offset1:27
	s_waitcnt lgkmcnt(4)
	ds_read2_b32 v[240:241], v186 offset0:32 offset1:33
	ds_read2_b32 v[242:243], v186 offset0:34 offset1:35
	ds_read2_b32 v[244:245], v186 offset0:40 offset1:41
	ds_read2_b32 v[246:247], v186 offset0:42 offset1:43
	ds_read2_b32 v[248:249], v186 offset0:48 offset1:49
	ds_read2_b32 v[250:251], v186 offset0:50 offset1:51
	ds_read2_b32 v[188:189], v186 offset0:56 offset1:57
	ds_read2_b32 v[190:191], v186 offset0:58 offset1:59
	s_waitcnt lgkmcnt(8)
	v_add_f32_e32 v112, v112, v224
	v_add_f32_e32 v113, v113, v225
	v_add_f32_e32 v114, v114, v226
	v_add_f32_e32 v115, v115, v227
	v_add_f32_e32 v116, v116, v228
	v_add_f32_e32 v117, v117, v229
	v_add_f32_e32 v118, v118, v230
	v_add_f32_e32 v119, v119, v231
	v_add_f32_e32 v120, v120, v232
	v_add_f32_e32 v121, v121, v233
	v_add_f32_e32 v122, v122, v234
	v_add_f32_e32 v123, v123, v235
	v_add_f32_e32 v124, v124, v236
	v_add_f32_e32 v125, v125, v237
	v_add_f32_e32 v126, v126, v238
	v_add_f32_e32 v127, v127, v239
	s_waitcnt lgkmcnt(0)
	v_add_f32_e32 v192, v192, v240
	v_add_f32_e32 v193, v193, v241
	v_add_f32_e32 v194, v194, v242
	v_add_f32_e32 v195, v195, v243
	v_add_f32_e32 v196, v196, v244
	v_add_f32_e32 v197, v197, v245
	v_add_f32_e32 v198, v198, v246
	v_add_f32_e32 v199, v199, v247
	v_add_f32_e32 v200, v200, v248
	v_add_f32_e32 v201, v201, v249
	v_add_f32_e32 v202, v202, v250
	v_add_f32_e32 v203, v203, v251
	v_add_f32_e32 v204, v204, v188
	v_add_f32_e32 v205, v205, v189
	v_add_f32_e32 v206, v206, v190
	v_add_f32_e32 v207, v207, v191
; #define SBAR() __builtin_amdgcn_sched_barrier(0)
; #define PVLOAD(D0, X) do { X[0] = tr_read<v_rd_off(D0, 0, 0)>(vb); X[1] = tr_read<v_rd_off(D0, 0, 1)>(vb); X[2] = tr_read<v_rd_off(D0, 1, 0)>(vb); X[3] = tr_read<v_rd_off(D0, 1, 1)>(vb); \
;     X[4] = tr_read<v_rd_off(D0, 2, 0)>(vb); X[5] = tr_read<v_rd_off(D0, 2, 1)>(vb); X[6] = tr_read<v_rd_off(D0, 3, 0)>(vb); X[7] = tr_read<v_rd_off(D0, 3, 1)>(vb); } while (0)
; #define PVMMA(OD, X) do { OD = __builtin_amdgcn_mfma_f32_32x32x16_bf16(pa0, PVPK(X[0], X[1]), OD, 0, 0, 0); OD = __builtin_amdgcn_mfma_f32_32x32x16_bf16(pa1, PVPK(X[2], X[3]), OD, 0, 0, 0); \
;     OD = __builtin_amdgcn_mfma_f32_32x32x16_bf16(pa2, PVPK(X[4], X[5]), OD, 0, 0, 0); OD = __builtin_amdgcn_mfma_f32_32x32x16_bf16(pa3, PVPK(X[6], X[7]), OD, 0, 0, 0); } while (0)
; #define PVWAIT() do { asm volatile("s_waitcnt lgkmcnt(0)" ::: "memory"); SBAR(); } while (0)
; #define PVEXP(P, B, N) do { _Pragma("unroll") for (int r = (B); r < (B) + (N); ++r) P[r] = __builtin_amdgcn_exp2f(P[r]); } while (0)
; #define QK(P0, P1, KS, t) do { float v_ = -A.mshift; if (MODE == 0) { const int z_ = zone_of(t); v_ += (z_ == 0 ? A.farL : (z_ == 2 ? A.farR : 0.f)); } \
;     qkt(P0, P1, KS, qr, v_, r32, hi, half); } while (0)
; template <int NB> __device__ __forceinline__ void pv_blocks(f32x16* o, int vb, bf16x8 pa0, bf16x8 pa1, bf16x8 pa2, bf16x8 pa3, f32x16& pe0, f32x16& pe1) {
;     s16x4 x[8], y[8];
;     ...
;     PVLOAD(0, x); PVWAIT();
;     if (NB == 4) {
;         PVLOAD(1, y); SBAR(); PVMMA(o[0], x); PVEXP(pe0, 0, 8); SBAR(); PVWAIT();
;         PVLOAD(2, x); SBAR(); PVMMA(o[1], y); PVEXP(pe0, 8, 8); SBAR(); PVWAIT();
;         PVLOAD(3, y); SBAR(); PVMMA(o[2], x); PVEXP(pe1, 0, 8); SBAR(); PVWAIT();
;         PVMMA(o[3], y); PVEXP(pe1, 8, 8);
;     } else {
;         PVLOAD(1, y); SBAR(); PVMMA(o[0], x); PVEXP(pe0, 0, 16); SBAR(); PVWAIT();
;         PVMMA(o[1], y); PVEXP(pe1, 0, 16);
;     }
;     ...
; }
; template <int MODE>
; __device__ __forceinline__ void attn_unit(const UnitArgs& A, char* lds, const int wave_) {
;     ...
;     SBAR(); QK(pB0, pB1, K_lds + SHM_K, NT - 1);
;     finishSM(pA0, pA1, l_reg, pa0, pa1, pa2, pa3); SBAR();
;     post(pB0, pB1, NT - 1); PV(0, pB0, pB1);
;     finishSM(pB0, pB1, l_reg, pa0, pa1, pa2, pa3); SBAR();
;     PV(1, pA0, pA1);
.Lat_far_g1p:
	v_exp_f32_e32 v112, v112
	v_exp_f32_e32 v113, v113
	v_exp_f32_e32 v114, v114
	v_exp_f32_e32 v115, v115
	v_exp_f32_e32 v116, v116
	v_exp_f32_e32 v117, v117
	v_exp_f32_e32 v118, v118
	v_exp_f32_e32 v119, v119
	v_exp_f32_e32 v120, v120
	v_exp_f32_e32 v121, v121
	v_exp_f32_e32 v122, v122
	v_exp_f32_e32 v123, v123
	v_exp_f32_e32 v124, v124
	v_exp_f32_e32 v125, v125
	v_exp_f32_e32 v126, v126
	v_exp_f32_e32 v127, v127
	v_exp_f32_e32 v192, v192
	v_add_f32_e32 v64, v64, v112
	v_exp_f32_e32 v193, v193
	v_add_f32_e32 v65, v65, v113
	v_exp_f32_e32 v194, v194
	v_add_f32_e32 v66, v66, v114
	v_exp_f32_e32 v195, v195
	v_add_f32_e32 v67, v67, v115
	v_exp_f32_e32 v196, v196
	v_add_f32_e32 v64, v64, v116
	v_exp_f32_e32 v197, v197
	v_add_f32_e32 v65, v65, v117
	v_exp_f32_e32 v198, v198
	v_add_f32_e32 v66, v66, v118
	v_exp_f32_e32 v199, v199
	v_add_f32_e32 v67, v67, v119
	v_exp_f32_e32 v200, v200
	v_add_f32_e32 v64, v64, v120
	v_exp_f32_e32 v201, v201
	v_add_f32_e32 v65, v65, v121
	v_exp_f32_e32 v202, v202
	v_add_f32_e32 v66, v66, v122
	v_exp_f32_e32 v203, v203
	v_add_f32_e32 v67, v67, v123
	v_exp_f32_e32 v204, v204
	v_add_f32_e32 v64, v64, v124
	v_exp_f32_e32 v205, v205
	v_add_f32_e32 v65, v65, v125
	v_exp_f32_e32 v206, v206
	v_add_f32_e32 v66, v66, v126
	v_exp_f32_e32 v207, v207
	v_add_f32_e32 v67, v67, v127
	v_cvt_pk_bf16_f32 v208, v112, v113
	v_cvt_pk_bf16_f32 v209, v114, v115
	v_cvt_pk_bf16_f32 v210, v116, v117
	v_cvt_pk_bf16_f32 v211, v118, v119
	v_cvt_pk_bf16_f32 v212, v120, v121
	v_cvt_pk_bf16_f32 v213, v122, v123
	v_cvt_pk_bf16_f32 v214, v124, v125
	v_cvt_pk_bf16_f32 v215, v126, v127
	v_add_f32_e32 v64, v64, v192
	v_add_f32_e32 v65, v65, v193
	v_add_f32_e32 v66, v66, v194
	v_add_f32_e32 v67, v67, v195
	v_add_f32_e32 v64, v64, v196
	v_add_f32_e32 v65, v65, v197
	v_add_f32_e32 v66, v66, v198
	v_add_f32_e32 v67, v67, v199
	v_add_f32_e32 v64, v64, v200
	v_add_f32_e32 v65, v65, v201
	v_add_f32_e32 v66, v66, v202
	v_add_f32_e32 v67, v67, v203
	v_add_f32_e32 v64, v64, v204
	v_add_f32_e32 v65, v65, v205
	v_add_f32_e32 v66, v66, v206
	v_add_f32_e32 v67, v67, v207
	v_cvt_pk_bf16_f32 v216, v192, v193
	v_cvt_pk_bf16_f32 v217, v194, v195
	v_cvt_pk_bf16_f32 v218, v196, v197
	v_cvt_pk_bf16_f32 v219, v198, v199
	v_cvt_pk_bf16_f32 v220, v200, v201
	v_cvt_pk_bf16_f32 v221, v202, v203
	v_cvt_pk_bf16_f32 v222, v204, v205
	v_cvt_pk_bf16_f32 v223, v206, v207
	s_nop 1
	s_waitcnt vmcnt(0)
	s_barrier
	s_setprio 0
	ds_read_b64_tr_b16 v[84:85], v168 offset:0
	ds_read_b64_tr_b16 v[86:87], v168 offset:2048
	ds_read_b64_tr_b16 v[88:89], v168 offset:4096
	ds_read_b64_tr_b16 v[90:91], v168 offset:6144
	ds_read_b64_tr_b16 v[92:93], v168 offset:8192
	ds_read_b64_tr_b16 v[94:95], v168 offset:10240
	ds_read_b64_tr_b16 v[128:129], v168 offset:12288
	ds_read_b64_tr_b16 v[130:131], v168 offset:14336
	ds_read_b64_tr_b16 v[132:133], v168 offset:512
	ds_read_b64_tr_b16 v[134:135], v168 offset:2560
	ds_read_b64_tr_b16 v[140:141], v168 offset:4608
	ds_read_b64_tr_b16 v[142:143], v168 offset:6656
	ds_read_b64_tr_b16 v[152:153], v168 offset:8704
	ds_read_b64_tr_b16 v[154:155], v168 offset:10752
	s_waitcnt lgkmcnt(12)
	v_mfma_f32_32x32x16_bf16 v[0:15], v[208:211], v[84:87], v[0:15]
	ds_read_b64_tr_b16 v[160:161], v168 offset:12800
	ds_read_b64_tr_b16 v[162:163], v168 offset:14848
	s_waitcnt lgkmcnt(12)
	v_mfma_f32_32x32x16_bf16 v[0:15], v[212:215], v[88:91], v[0:15]
	ds_read_b64_tr_b16 v[84:85], v168 offset:1024
	ds_read_b64_tr_b16 v[86:87], v168 offset:3072
	s_waitcnt lgkmcnt(12)
	v_mfma_f32_32x32x16_bf16 v[0:15], v[216:219], v[92:95], v[0:15]
	ds_read_b64_tr_b16 v[88:89], v168 offset:5120
	ds_read_b64_tr_b16 v[90:91], v168 offset:7168
	s_waitcnt lgkmcnt(12)
	v_mfma_f32_32x32x16_bf16 v[0:15], v[220:223], v[128:131], v[0:15]
	ds_read_b64_tr_b16 v[92:93], v168 offset:9216
	ds_read_b64_tr_b16 v[94:95], v168 offset:11264
	s_waitcnt lgkmcnt(12)
	v_mfma_f32_32x32x16_bf16 v[16:31], v[208:211], v[132:135], v[16:31]
	ds_read_b64_tr_b16 v[128:129], v168 offset:13312
	ds_read_b64_tr_b16 v[130:131], v168 offset:15360
	s_waitcnt lgkmcnt(12)
	v_mfma_f32_32x32x16_bf16 v[16:31], v[212:215], v[140:143], v[16:31]
	ds_read_b64_tr_b16 v[132:133], v168 offset:1536
	ds_read_b64_tr_b16 v[134:135], v168 offset:3584
	s_waitcnt lgkmcnt(12)
	v_mfma_f32_32x32x16_bf16 v[16:31], v[216:219], v[152:155], v[16:31]
	ds_read_b64_tr_b16 v[140:141], v168 offset:5632
	ds_read_b64_tr_b16 v[142:143], v168 offset:7680
	s_waitcnt lgkmcnt(12)
	v_mfma_f32_32x32x16_bf16 v[16:31], v[220:223], v[160:163], v[16:31]
	ds_read_b64_tr_b16 v[152:153], v168 offset:9728
	ds_read_b64_tr_b16 v[154:155], v168 offset:11776
	s_waitcnt lgkmcnt(12)
	v_mfma_f32_32x32x16_bf16 v[32:47], v[208:211], v[84:87], v[32:47]
	ds_read_b64_tr_b16 v[160:161], v168 offset:13824
	ds_read_b64_tr_b16 v[162:163], v168 offset:15872
	v_xor_b32_e32 v168, 0x4000, v168
	s_waitcnt lgkmcnt(12)
	v_mfma_f32_32x32x16_bf16 v[32:47], v[212:215], v[88:91], v[32:47]
	s_waitcnt lgkmcnt(10)
	v_mfma_f32_32x32x16_bf16 v[32:47], v[216:219], v[92:95], v[32:47]
	s_waitcnt lgkmcnt(8)
	v_mfma_f32_32x32x16_bf16 v[32:47], v[220:223], v[128:131], v[32:47]
	s_waitcnt lgkmcnt(6)
	v_mfma_f32_32x32x16_bf16 v[48:63], v[208:211], v[132:135], v[48:63]
	s_waitcnt lgkmcnt(4)
	v_mfma_f32_32x32x16_bf16 v[48:63], v[212:215], v[140:143], v[48:63]
	s_waitcnt lgkmcnt(2)
	v_mfma_f32_32x32x16_bf16 v[48:63], v[216:219], v[152:155], v[48:63]
	s_waitcnt lgkmcnt(0)
	v_mfma_f32_32x32x16_bf16 v[48:63], v[220:223], v[160:163], v[48:63]
	s_waitcnt vmcnt(0)
	s_barrier
